# RG-LRU prologue: w_a/w_x fragment gathers issued by wave 0 only and shared through LDS (other waves exec-masked), on top of the step-1 re-split, LRU prefetch placement and S5 blocked scan
# speedup vs baseline: 1.0025x; 1.0001x over previous
; __device__ __forceinline__ unsigned cvt_pk_bf16_pure(float lo, float hi) { unsigned r; asm("v_cvt_pk_bf16_f32 %0, %1, %2" : "=v"(r) : "v"(lo), "v"(hi)); return r; }
; __device__ __forceinline__ void lru_item(const Args& a, LAS unsigned char* lds, bool sample, int b, int head, int q, int tid, int lane, int wave) {
;     ...
;     bf16x8 Bf[2][2];
; #pragma unroll
;     for (int mat = 0; mat < 2; ++mat)
; #pragma unroll
;         for (int ks = 0; ks < 2; ++ks) {
;             const float* w = (mat ? a.in[I_WX] : a.in[I_WA]) + ((size_t)(head * 64 + 32 * ks + 8 * fq)) * 64 + 16 * q + fr;
;             u32x4 p; p.x = cvt_pk_bf16_pure(w[0], w[64]); p.y = cvt_pk_bf16_pure(w[128], w[192]); p.z = cvt_pk_bf16_pure(w[256], w[320]); p.w = cvt_pk_bf16_pure(w[384], w[448]);
;             Bf[mat][ks] = __builtin_bit_cast(bf16x8, p);
;         }
;     const int chn = ch0 + fr;
;     const float ba = a.in[I_BA][chn], bx_ = a.in[I_BX][chn], laml = a.in[I_LAML][chn];
;     const int cq = tid & 15, cch = 64 * head + 4 * cq, rg = tid >> 4;
;     const f32x4 cw0 = *(const f32x4*)(a.in[I_CONVW] + cch), cw1 = *(const f32x4*)(a.in[I_CONVW] + DH + cch), cw2 = *(const f32x4*)(a.in[I_CONVW] + 2 * DH + cch),
;                 cw3 = *(const f32x4*)(a.in[I_CONVW] + 3 * DH + cch), cb = *(const f32x4*)(a.in[I_CONVB] + cch);
;     const int er = tid >> 1, eh = tid & 1;
;     f32x4 xin[11]; u32x4 ggn;
;     if (!sample) {
;         const int R0 = b * SEQ, r0 = rg * 8;
; #pragma unroll
;         for (int i = 0; i < 11; ++i) { const int t = r0 + i - 3; xin[i] = *(const f32x4*)(XL + (size_t)(R0 + (t >= 0 ? t : 0)) * DH + cch); }
;         ggn = *(const u32x4*)(GG + (size_t)(R0 + er) * DH + ch0 + 8 * eh);
;     }
.LBB0_671:
	s_lshl_b32 s30, s70, 1
	s_bfe_u32 s9, s70, 0x10005
	s_bfe_u32 s8, s70, 0x20003
	s_and_b32 s30, s30, 14
	s_or_b32 s37, s30, s9
	s_lshl_b32 s30, s8, 6
	v_lshl_or_b32 v2, s37, 14, v170
	v_mov_b32_e32 v3, v99
	v_lshl_add_u64 v[4:5], v[100:101], 0, s[30:31]
	v_lshl_add_u64 v[6:7], v[4:5], 0, v[2:3]
	v_readlane_b32 s100, v254, 12
	s_cmp_lt_u32 s100, 64
	s_cselect_b64 s[100:101], -1, 0
	s_mov_b64 exec, s[100:101]
	global_load_dword v8, v[6:7], off
	global_load_dword v9, v[6:7], off offset:256
	global_load_dword v10, v[6:7], off offset:512
	global_load_dword v11, v[6:7], off offset:768
	global_load_dword v12, v[6:7], off offset:1024
	global_load_dword v13, v[6:7], off offset:1280
	global_load_dword v14, v[6:7], off offset:1536
	global_load_dword v15, v[6:7], off offset:1792
	s_mov_b64 exec, -1
	v_or_b32_e32 v6, 0x2000, v2
	v_mov_b32_e32 v7, v99
	v_lshl_add_u64 v[4:5], v[4:5], 0, v[6:7]
	s_mov_b64 exec, s[100:101]
	global_load_dword v16, v[4:5], off
	global_load_dword v17, v[4:5], off offset:256
	global_load_dword v40, v[4:5], off offset:512
	global_load_dword v41, v[4:5], off offset:768
	global_load_dword v42, v[4:5], off offset:1024
	global_load_dword v43, v[4:5], off offset:1280
	global_load_dword v44, v[4:5], off offset:1536
	global_load_dword v45, v[4:5], off offset:1792
	s_mov_b64 exec, -1
	v_lshl_add_u64 v[4:5], v[102:103], 0, s[30:31]
	v_lshl_add_u64 v[2:3], v[4:5], 0, v[2:3]
	s_mov_b64 exec, s[100:101]
	global_load_dword v46, v[2:3], off
	global_load_dword v47, v[2:3], off offset:256
	global_load_dword v48, v[2:3], off offset:512
	global_load_dword v49, v[2:3], off offset:768
	global_load_dword v50, v[2:3], off offset:1024
	global_load_dword v51, v[2:3], off offset:1280
	global_load_dword v52, v[2:3], off offset:1536
	global_load_dword v53, v[2:3], off offset:1792
	s_mov_b64 exec, -1
	s_lshl_b32 s30, s12, 7
	s_lshl_b32 s9, s9, 7
	s_and_b32 s30, s30, 0x700
	s_lshl_b32 s36, s8, 5
	s_or_b32 s9, s30, s9
	s_lshl_b32 s45, s8, 4
	s_or_b32 s36, s36, s9
	s_lshl_b32 s9, s37, 6
	v_lshl_add_u64 v[2:3], v[4:5], 0, v[6:7]
	s_or_b32 s71, s9, s45
	s_mov_b64 exec, s[100:101]
	global_load_dword v54, v[2:3], off
	global_load_dword v55, v[2:3], off offset:256
	global_load_dword v56, v[2:3], off offset:512
	global_load_dword v57, v[2:3], off offset:768
	global_load_dword v58, v[2:3], off offset:1024
	global_load_dword v59, v[2:3], off offset:1280
	global_load_dword v60, v[2:3], off offset:1536
	global_load_dword v61, v[2:3], off offset:1792
	s_mov_b64 exec, -1
	v_or_b32_e32 v2, s9, v96
	v_or_b32_e32 v3, s71, v90
	v_readlane_b32 s48, v254, 47
	v_lshlrev_b32_e32 v38, 2, v2
	v_lshlrev_b32_e32 v2, 2, v3
	v_readlane_b32 s50, v254, 49
	v_readlane_b32 s51, v254, 50
	global_load_dwordx4 v[26:29], v38, s[4:5]
	global_load_dwordx4 v[22:25], v38, s[20:21]
	global_load_dwordx4 v[18:21], v38, s[22:23]
	v_readlane_b32 s54, v254, 53
	v_readlane_b32 s55, v254, 54
	v_readlane_b32 s56, v254, 55
	v_readlane_b32 s57, v254, 56
	global_load_dword v97, v2, s[50:51]
	s_nop 1
	global_load_dword v93, v2, s[54:55]
	s_nop 0
	global_load_dword v86, v2, s[56:57]
	v_readlane_b32 s49, v254, 48
	v_readlane_b32 s52, v254, 51
	v_readlane_b32 s53, v254, 52
	v_readlane_b32 s58, v254, 57
	v_readlane_b32 s59, v254, 58
	v_readlane_b32 s60, v254, 59
	v_readlane_b32 s61, v254, 60
	v_readlane_b32 s62, v254, 61
	v_readlane_b32 s63, v254, 62
	v_readlane_b32 s48, v254, 20
	s_ashr_i32 s44, s70, 6
	v_readlane_b32 s49, v254, 21
	v_readlane_b32 s50, v254, 22
	v_readlane_b32 s51, v254, 23
	v_readlane_b32 s60, v254, 32
	v_readlane_b32 s61, v254, 33
	v_mov_b32_e32 v39, v99
	v_readlane_b32 s62, v254, 34
	v_readlane_b32 s63, v254, 35
	s_mov_b64 s[48:49], s[60:61]
	s_lshl_b32 s72, s44, 11
	s_mov_b64 s[50:51], s[62:63]
	global_load_dwordx4 v[30:33], v38, s[48:49]
	global_load_dwordx4 v[34:37], v38, s[50:51]
	v_lshl_add_u64 v[110:111], s[10:11], 0, v[38:39]
	v_or_b32_e32 v38, s72, v91
	v_ashrrev_i32_e32 v39, 31, v38
	v_lshlrev_b64 v[38:39], 12, v[38:39]
	v_lshl_add_u64 v[38:39], v[110:111], 0, v[38:39]
	v_readlane_b32 s46, v254, 63
	v_readlane_b32 s47, v253, 0
	s_lshl_b32 s30, s71, 1
	v_cmp_eq_u32_e64 s[8:9], s8, v136
	v_or_b32_e32 v181, s72, v171
	v_or_b32_e32 v182, s72, v172
	v_readlane_b32 s52, v254, 24
	v_readlane_b32 s53, v254, 25
	v_readlane_b32 s54, v254, 26
	s_waitcnt vmcnt(38)
	v_cvt_pk_bf16_f32 v2, v8, v9
	s_waitcnt vmcnt(32)
	v_cvt_pk_bf16_f32 v5, v14, v15
	s_waitcnt vmcnt(28)
	v_cvt_pk_bf16_f32 v15, v40, v41
	v_or_b32_e32 v40, s72, v134
	v_ashrrev_i32_e32 v41, 31, v40
	v_lshlrev_b64 v[40:41], 12, v[40:41]
	v_cvt_pk_bf16_f32 v3, v10, v11
	s_waitcnt vmcnt(18)
	v_cvt_pk_bf16_f32 v8, v50, v51
	s_waitcnt vmcnt(16)
	v_cvt_pk_bf16_f32 v9, v52, v53
	s_waitcnt vmcnt(14)
	v_cvt_pk_bf16_f32 v10, v54, v55
	v_lshl_add_u64 v[40:41], v[110:111], 0, v[40:41]
	global_load_dwordx4 v[50:53], v[38:39], off
	global_load_dwordx4 v[82:85], v[40:41], off
	v_or_b32_e32 v38, s72, v135
	v_or_b32_e32 v54, s72, v1
	v_ashrrev_i32_e32 v39, 31, v38
	v_ashrrev_i32_e32 v55, 31, v54
	v_lshlrev_b64 v[38:39], 12, v[38:39]
	v_lshlrev_b64 v[40:41], 12, v[54:55]
	v_lshl_add_u64 v[38:39], v[110:111], 0, v[38:39]
	v_lshl_add_u64 v[40:41], v[110:111], 0, v[40:41]
	global_load_dwordx4 v[78:81], v[38:39], off
	global_load_dwordx4 v[70:73], v[40:41], off
	v_or_b32_e32 v38, 1, v54
	v_or_b32_e32 v40, 2, v54
	v_ashrrev_i32_e32 v39, 31, v38
	v_ashrrev_i32_e32 v41, 31, v40
	s_waitcnt vmcnt(16)
	v_cvt_pk_bf16_f32 v11, v56, v57
	v_lshlrev_b64 v[38:39], 12, v[38:39]
	v_lshlrev_b64 v[40:41], 12, v[40:41]
	v_or_b32_e32 v56, s72, v162
	v_lshl_add_u64 v[38:39], v[110:111], 0, v[38:39]
	v_lshl_add_u64 v[40:41], v[110:111], 0, v[40:41]
	v_ashrrev_i32_e32 v57, 31, v56
	s_waitcnt vmcnt(6)
; __device__ __forceinline__ unsigned cvt_pk_bf16_pure(float lo, float hi) { unsigned r; asm("v_cvt_pk_bf16_f32 %0, %1, %2" : "=v"(r) : "v"(lo), "v"(hi)); return r; }
; __device__ __forceinline__ void lru_item(const Args& a, LAS unsigned char* lds, bool sample, int b, int head, int q, int tid, int lane, int wave) {
;     ...
;     for (int mat = 0; mat < 2; ++mat)
; #pragma unroll
;         for (int ks = 0; ks < 2; ++ks) {
;             const float* w = (mat ? a.in[I_WX] : a.in[I_WA]) + ((size_t)(head * 64 + 32 * ks + 8 * fq)) * 64 + 16 * q + fr;
;             u32x4 p; p.x = cvt_pk_bf16_pure(w[0], w[64]); p.y = cvt_pk_bf16_pure(w[128], w[192]); p.z = cvt_pk_bf16_pure(w[256], w[320]); p.w = cvt_pk_bf16_pure(w[384], w[448]);
;             Bf[mat][ks] = __builtin_bit_cast(bf16x8, p);
;         }
;     const int chn = ch0 + fr;
;     const float ba = a.in[I_BA][chn], bx_ = a.in[I_BX][chn], laml = a.in[I_LAML][chn];
;     const int cq = tid & 15, cch = 64 * head + 4 * cq, rg = tid >> 4;
;     const f32x4 cw0 = *(const f32x4*)(a.in[I_CONVW] + cch), cw1 = *(const f32x4*)(a.in[I_CONVW] + DH + cch), cw2 = *(const f32x4*)(a.in[I_CONVW] + 2 * DH + cch),
;                 cw3 = *(const f32x4*)(a.in[I_CONVW] + 3 * DH + cch), cb = *(const f32x4*)(a.in[I_CONVB] + cch);
;     const int er = tid >> 1, eh = tid & 1;
;     f32x4 xin[11]; u32x4 ggn;
;     if (!sample) {
;         const int R0 = b * SEQ, r0 = rg * 8;
; #pragma unroll
;         for (int i = 0; i < 11; ++i) { const int t = r0 + i - 3; xin[i] = *(const f32x4*)(XL + (size_t)(R0 + (t >= 0 ? t : 0)) * DH + cch); }
;         ggn = *(const u32x4*)(GG + (size_t)(R0 + er) * DH + ch0 + 8 * eh);
;     }
;     const float spl = log1pf(expf(-laml));
;     if (!sample) {
;         float hcar = 0.f;
;         if (rg == 0) { xin[0] = (f32x4){0.f, 0.f, 0.f, 0.f}; xin[1] = xin[0]; xin[2] = xin[0]; }
	v_mul_f32_e32 v74, 0xbfb8aa3b, v86
	v_cvt_pk_bf16_f32 v14, v16, v17
	v_cvt_pk_bf16_f32 v16, v42, v43
	v_cvt_pk_bf16_f32 v17, v44, v45
	global_load_dwordx4 v[66:69], v[38:39], off
	global_load_dwordx4 v[62:65], v[40:41], off
	v_or_b32_e32 v38, 3, v54
	v_or_b32_e32 v40, 4, v54
	v_or_b32_e32 v42, 5, v54
	v_or_b32_e32 v44, 6, v54
	v_or_b32_e32 v54, 7, v54
	v_lshlrev_b64 v[56:57], 11, v[56:57]
	v_fma_f32 v75, v86, s28, -v74
	v_rndne_f32_e32 v76, v74
	v_ashrrev_i32_e32 v39, 31, v38
	v_ashrrev_i32_e32 v41, 31, v40
	v_ashrrev_i32_e32 v43, 31, v42
	v_ashrrev_i32_e32 v45, 31, v44
	v_ashrrev_i32_e32 v55, 31, v54
	v_lshl_add_u64 v[56:57], s[46:47], 0, v[56:57]
	v_fmac_f32_e32 v75, 0xb2a5705f, v86
	v_sub_f32_e32 v74, v74, v76
	v_lshlrev_b64 v[38:39], 12, v[38:39]
	v_lshlrev_b64 v[40:41], 12, v[40:41]
	v_lshlrev_b64 v[42:43], 12, v[42:43]
	v_lshlrev_b64 v[44:45], 12, v[44:45]
	v_lshlrev_b64 v[54:55], 12, v[54:55]
	v_lshl_add_u64 v[56:57], v[56:57], 0, s[30:31]
	v_add_f32_e32 v74, v74, v75
	v_lshl_add_u64 v[38:39], v[110:111], 0, v[38:39]
	v_lshl_add_u64 v[40:41], v[110:111], 0, v[40:41]
	v_lshl_add_u64 v[42:43], v[110:111], 0, v[42:43]
	v_lshl_add_u64 v[44:45], v[110:111], 0, v[44:45]
	v_lshl_add_u64 v[54:55], v[110:111], 0, v[54:55]
	v_exp_f32_e32 v87, v74
	v_lshl_add_u64 v[74:75], v[56:57], 0, v[98:99]
	v_cvt_pk_bf16_f32 v4, v12, v13
	v_cvt_pk_bf16_f32 v6, v46, v47
	v_cvt_pk_bf16_f32 v7, v48, v49
	v_cvt_pk_bf16_f32 v12, v58, v59
	v_cvt_pk_bf16_f32 v13, v60, v61
	global_load_dwordx4 v[58:61], v[38:39], off
	s_nop 0
	global_load_dwordx4 v[38:41], v[40:41], off
	s_nop 0
	global_load_dwordx4 v[46:49], v[42:43], off
	s_nop 0
	global_load_dwordx4 v[42:45], v[44:45], off
	v_cvt_i32_f32_e32 v88, v76
	global_load_dwordx4 v[54:57], v[54:55], off
	s_nop 0
	global_load_dwordx4 v[74:77], v[74:75], off
	v_cmp_nlt_f32_e32 vcc, s29, v86
	v_readlane_b32 s55, v254, 27
	v_ldexp_f32 v87, v87, v88
	v_cndmask_b32_e32 v87, 0, v87, vcc
	v_cmp_ngt_f32_e32 vcc, s33, v86
	v_readlane_b32 s56, v254, 28
	v_readlane_b32 s57, v254, 29
	v_cndmask_b32_e32 v88, v174, v87, vcc
	v_add_f32_e32 v89, 1.0, v88
	v_add_f32_e32 v86, -1.0, v89
	v_sub_f32_e32 v87, v86, v89
	v_add_f32_e32 v87, 1.0, v87
	v_sub_f32_e32 v86, v88, v86
	v_add_f32_e32 v108, v86, v87
	v_frexp_mant_f32_e32 v109, v89
	v_cvt_f64_f32_e32 v[86:87], v89
	v_frexp_exp_i32_f64_e32 v86, v[86:87]
	v_cmp_gt_f32_e32 vcc, s35, v109
	s_waitcnt vmcnt(10)
	v_cndmask_b32_e64 v85, v85, 0, s[0:1]
	v_cndmask_b32_e64 v84, v84, 0, s[0:1]
	v_subbrev_co_u32_e32 v86, vcc, 0, v86, vcc
	v_sub_u32_e32 v87, 0, v86
	v_ldexp_f32 v89, v89, v87
	v_ldexp_f32 v87, v108, v87
	v_add_f32_e32 v108, -1.0, v89
	v_add_f32_e32 v113, 1.0, v89
	v_add_f32_e32 v109, 1.0, v108
	v_add_f32_e32 v114, -1.0, v113
	v_sub_f32_e32 v109, v89, v109
	v_sub_f32_e32 v89, v89, v114
	v_add_f32_e32 v109, v87, v109
	v_add_f32_e32 v87, v87, v89
	v_add_f32_e32 v89, v113, v87
	v_rcp_f32_e32 v114, v89
	v_add_f32_e32 v112, v108, v109
	v_sub_f32_e32 v108, v108, v112
	v_add_f32_e32 v108, v109, v108
	v_sub_f32_e32 v109, v113, v89
	v_add_f32_e32 v87, v87, v109
	v_mul_f32_e32 v109, v112, v114
	v_mul_f32_e32 v113, v89, v109
	v_fma_f32 v115, v109, v89, -v113
	v_fmac_f32_e32 v115, v109, v87
	v_add_f32_e32 v116, v113, v115
	v_sub_f32_e32 v117, v112, v116
	v_sub_f32_e32 v112, v112, v117
	v_sub_f32_e32 v113, v116, v113
	v_sub_f32_e32 v112, v112, v116
	v_add_f32_e32 v108, v108, v112
	v_sub_f32_e32 v112, v113, v115
	v_add_f32_e32 v108, v112, v108
	v_add_f32_e32 v112, v117, v108
	v_mul_f32_e32 v113, v114, v112
	v_mul_f32_e32 v115, v89, v113
	v_fma_f32 v89, v113, v89, -v115
	v_fmac_f32_e32 v89, v113, v87
	v_sub_f32_e32 v87, v117, v112
	v_add_f32_e32 v87, v108, v87
	v_add_f32_e32 v108, v115, v89
	v_sub_f32_e32 v116, v112, v108
	v_sub_f32_e32 v112, v112, v116
	v_sub_f32_e32 v115, v108, v115
	v_sub_f32_e32 v108, v112, v108
	v_add_f32_e32 v87, v87, v108
	v_sub_f32_e32 v89, v115, v89
	v_cvt_f32_i32_e32 v86, v86
	v_add_f32_e32 v87, v89, v87
	v_add_f32_e32 v89, v109, v113
	v_add_f32_e32 v87, v116, v87
	v_sub_f32_e32 v108, v89, v109
	v_mul_f32_e32 v87, v114, v87
	v_sub_f32_e32 v108, v113, v108
	v_add_f32_e32 v87, v108, v87
	v_mul_f32_e32 v113, 0x3f317218, v86
	v_add_f32_e32 v108, v89, v87
	v_fma_f32 v114, v86, s68, -v113
	v_mul_f32_e32 v109, v108, v108
	v_fmac_f32_e32 v114, 0xb102e308, v86
	v_sub_f32_e32 v86, v108, v89
	v_fmamk_f32 v112, v109, 0x3e9b6dac, v173
	v_sub_f32_e32 v86, v87, v86
	v_add_f32_e32 v87, v113, v114
	v_fmaak_f32 v112, v109, v112, 0x3f2aaada
	v_sub_f32_e32 v89, v87, v113
	v_ldexp_f32 v113, v108, 1
	v_mul_f32_e32 v108, v108, v109
	v_mul_f32_e32 v108, v108, v112
	v_add_f32_e32 v109, v113, v108
	v_sub_f32_e32 v112, v109, v113
	v_ldexp_f32 v86, v86, 1
	v_sub_f32_e32 v108, v108, v112
	v_add_f32_e32 v86, v86, v108
	v_add_f32_e32 v108, v109, v86
	v_sub_f32_e32 v109, v108, v109
	v_sub_f32_e32 v86, v86, v109
	v_add_f32_e32 v109, v87, v108
	v_sub_f32_e32 v112, v109, v87
	v_sub_f32_e32 v113, v109, v112
	v_sub_f32_e32 v89, v114, v89
	v_sub_f32_e32 v87, v87, v113
	v_sub_f32_e32 v108, v108, v112
	v_add_f32_e32 v87, v108, v87
	v_add_f32_e32 v108, v89, v86
	v_sub_f32_e32 v112, v108, v89
	v_sub_f32_e32 v113, v108, v112
	v_sub_f32_e32 v89, v89, v113
	v_sub_f32_e32 v86, v86, v112
	v_add_f32_e32 v87, v108, v87
	v_add_f32_e32 v86, v86, v89
	v_add_f32_e32 v89, v109, v87
	v_sub_f32_e32 v108, v89, v109
	v_sub_f32_e32 v87, v87, v108
	v_add_f32_e32 v86, v86, v87
	v_add_f32_e32 v86, v89, v86
	v_cmp_neq_f32_e32 vcc, s34, v88
	v_lshl_add_u64 v[112:113], v[104:105], 0, s[30:31]
	s_ashr_i32 s30, s72, 31
	v_cndmask_b32_e32 v86, v174, v86, vcc
	v_cmp_lt_f32_e64 vcc, |v88|, s69
	v_cndmask_b32_e64 v87, v51, 0, s[0:1]
	v_mov_b32_e32 v51, s30
	v_cndmask_b32_e32 v180, v86, v88, vcc
	v_cndmask_b32_e64 v86, v50, 0, s[0:1]
	v_or_b32_e32 v50, s72, v162
	v_lshl_add_u64 v[114:115], v[50:51], 2, s[96:97]
	v_lshlrev_b64 v[50:51], 12, v[50:51]
	v_or_b32_e32 v50, s36, v50
	s_waitcnt vmcnt(1)
	v_cndmask_b32_e64 v81, v81, 0, s[0:1]
	v_cndmask_b32_e64 v80, v80, 0, s[0:1]
	v_cndmask_b32_e64 v79, v79, 0, s[0:1]
	v_cndmask_b32_e64 v78, v78, 0, s[0:1]
	v_cndmask_b32_e64 v83, v83, 0, s[0:1]
	v_cndmask_b32_e64 v82, v82, 0, s[0:1]
	v_cndmask_b32_e64 v89, v53, 0, s[0:1]
	v_cndmask_b32_e64 v88, v52, 0, s[0:1]
	v_lshl_add_u64 v[116:117], v[106:107], 0, v[50:51]
	s_mov_b32 s30, 0
	v_mov_b32_e32 v109, 0
	v_readlane_b32 s58, v254, 30
	v_readlane_b32 s59, v254, 31
	v_lshlrev_b32_e32 v230, 6, v210
	v_add_u32_e32 v230, 0x21000, v230
	s_mov_b64 exec, s[100:101]
	ds_write_b128 v230, v[2:5]
	ds_write_b128 v230, v[6:9] offset:16
	ds_write_b128 v230, v[10:13] offset:32
	ds_write_b128 v230, v[14:17] offset:48
	s_mov_b64 exec, -1
	s_waitcnt lgkmcnt(0)
	s_barrier
	ds_read_b128 v[2:5], v230
	ds_read_b128 v[6:9], v230 offset:16
	ds_read_b128 v[10:13], v230 offset:32
	ds_read_b128 v[14:17], v230 offset:48
	s_waitcnt lgkmcnt(0)
